# final RMSNorm loop: gains loaded once, all row loads issued together with one wait per row (was 8 serial load/wait/store rounds); on top of v9
# speedup vs baseline: 1.0086x; 1.0011x over previous
.LBB0_717:
	s_movk_i32 s0, 0x2000
	s_waitcnt vmcnt(0)
	v_ashrrev_i32_e32 v12, 6, v230
	v_add_u32_e32 v18, s24, v12
	v_cmp_gt_i32_e32 vcc, s0, v18
	s_and_saveexec_b64 s[0:1], vcc
	v_readlane_b32 s16, v250, 49
	v_readlane_b32 s17, v250, 50
	s_cbranch_execz .LBB0_720
	v_readlane_b32 s0, v250, 0
	v_ashrrev_i32_e32 v13, 31, v12
	s_ashr_i32 s25, s24, 31
	v_and_b32_e32 v19, 63, v230
	v_readlane_b32 s14, v250, 14
	v_readlane_b32 s15, v250, 15
	v_lshl_add_u64 v[16:17], v[12:13], 0, s[24:25]
	v_lshlrev_b32_e32 v0, 5, v19
	v_lshl_add_u64 v[12:13], v[16:17], 3, s[14:15]
	v_lshlrev_b64 v[14:15], 13, v[16:17]
	v_lshlrev_b64 v[16:17], 12, v[16:17]
	v_mov_b32_e32 v1, 0
	v_readlane_b32 s1, v250, 1
	v_readlane_b32 s2, v250, 2
	v_readlane_b32 s3, v250, 3
	v_readlane_b32 s4, v250, 4
	v_readlane_b32 s5, v250, 5
	v_readlane_b32 s8, v250, 8
	v_readlane_b32 s12, v250, 12
	v_readlane_b32 s13, v250, 13
	v_or_b32_e32 v14, v14, v0
	v_lshl_or_b32 v16, v19, 4, v16
	v_readlane_b32 s6, v250, 6
	v_readlane_b32 s7, v250, 7
	v_readlane_b32 s9, v250, 9
	v_readlane_b32 s10, v250, 10
	v_readlane_b32 s11, v250, 11
	v_or_b32_e32 v4, 0x1000, v0
	v_mov_b32_e32 v5, v1
	v_or_b32_e32 v6, 0x1010, v0
	v_mov_b32_e32 v7, v1
	v_or_b32_e32 v8, 0x1800, v0
	v_mov_b32_e32 v9, v1
	v_or_b32_e32 v10, 0x1810, v0
	v_mov_b32_e32 v11, v1
	s_mov_b64 s[0:1], 0x2d2a0000
	s_ashr_i32 s17, s16, 31
	v_lshl_add_u64 v[14:15], s[12:13], 0, v[14:15]
	s_mov_b64 s[2:3], 0x1000
	v_lshl_add_u64 v[16:17], s[14:15], 0, v[16:17]
	s_mov_b64 s[4:5], 0x1b020800
	s_min_u32 s8, s33, 32
	v_lshl_add_u64 v[2:3], s[10:11], 0, v[0:1]
	v_lshl_add_u64 v[4:5], s[10:11], 0, v[4:5]
	v_lshl_add_u64 v[6:7], s[10:11], 0, v[6:7]
	v_lshl_add_u64 v[8:9], s[10:11], 0, v[8:9]
	v_lshl_add_u64 v[10:11], s[10:11], 0, v[10:11]
	v_lshl_add_u64 v[12:13], v[12:13], 0, s[0:1]
	s_lshl_b64 s[0:1], s[16:17], 3
	v_lshl_add_u64 v[14:15], v[14:15], 0, s[2:3]
	s_lshl_b64 s[2:3], s[16:17], 13
	v_lshl_add_u64 v[16:17], v[16:17], 0, s[4:5]
	s_lshl_b64 s[4:5], s[16:17], 12
	s_mov_b64 s[6:7], 0
	s_sub_i32 s9, 32, s8
	v_mov_b32_e32 v19, 0x358637bd
	s_movk_i32 s10, 0x1fff
	global_load_dwordx4 v[60:63], v[2:3], off
	global_load_dwordx4 v[64:67], v[2:3], off offset:16
	global_load_dwordx4 v[68:71], v[2:3], off offset:2048
	global_load_dwordx4 v[72:75], v[2:3], off offset:2064
	global_load_dwordx4 v[76:79], v[4:5], off
	global_load_dwordx4 v[80:83], v[6:7], off
	global_load_dwordx4 v[84:87], v[8:9], off
	global_load_dwordx4 v[88:91], v[10:11], off
.LBB0_719:
	global_load_dwordx2 v[28:29], v[12:13], off
	global_load_dwordx4 v[40:43], v[16:17], off offset:-2048
	global_load_dwordx4 v[44:47], v[16:17], off offset:-1024
	global_load_dwordx4 v[48:51], v[16:17], off
	global_load_dwordx4 v[52:55], v[16:17], off offset:1024
	v_add_u32_e32 v18, s16, v18
	v_cmp_lt_i32_e32 vcc, s10, v18
	v_lshl_add_u64 v[12:13], v[12:13], 0, s[0:1]
	s_or_b64 s[6:7], vcc, s[6:7]
	v_lshl_add_u64 v[16:17], v[16:17], 0, s[4:5]
	s_waitcnt vmcnt(0)
	v_mov_b32_e32 v0, v29
	v_lshlrev_b64 v[30:31], s8, v[0:1]
	v_min_u32_e32 v0, 1, v30
	v_or_b32_e32 v0, v31, v0
	v_cvt_f32_u32_e32 v0, v0
	v_cvt_f32_u32_e32 v32, v28
	v_ldexp_f32 v0, v0, s9
	v_fmac_f32_e32 v32, 0x4f800000, v0
	v_fmamk_f32 v0, v32, 0x2e000000, v19
	v_rsq_f32_e32 v0, v0
	s_nop 0
	v_lshlrev_b32_e32 v20, 16, v40
	v_and_b32_e32 v21, 0xffff0000, v40
	v_lshlrev_b32_e32 v22, 16, v41
	v_and_b32_e32 v23, 0xffff0000, v41
	v_pk_mul_f32 v[20:21], v[0:1], v[20:21] op_sel_hi:[0,1]
	v_pk_mul_f32 v[22:23], v[0:1], v[22:23] op_sel_hi:[0,1]
	v_pk_mul_f32 v[24:25], v[60:61], v[20:21]
	v_pk_mul_f32 v[26:27], v[62:63], v[22:23]
	global_store_dwordx4 v[14:15], v[24:27], off offset:-4096
	v_lshlrev_b32_e32 v28, 16, v42
	v_and_b32_e32 v29, 0xffff0000, v42
	v_lshlrev_b32_e32 v30, 16, v43
	v_and_b32_e32 v31, 0xffff0000, v43
	v_pk_mul_f32 v[28:29], v[0:1], v[28:29] op_sel_hi:[0,1]
	v_pk_mul_f32 v[30:31], v[0:1], v[30:31] op_sel_hi:[0,1]
	v_pk_mul_f32 v[32:33], v[64:65], v[28:29]
	v_pk_mul_f32 v[34:35], v[66:67], v[30:31]
	global_store_dwordx4 v[14:15], v[32:35], off offset:-4080
	v_lshlrev_b32_e32 v20, 16, v44
	v_and_b32_e32 v21, 0xffff0000, v44
	v_lshlrev_b32_e32 v22, 16, v45
	v_and_b32_e32 v23, 0xffff0000, v45
	v_pk_mul_f32 v[20:21], v[0:1], v[20:21] op_sel_hi:[0,1]
	v_pk_mul_f32 v[22:23], v[0:1], v[22:23] op_sel_hi:[0,1]
	v_pk_mul_f32 v[24:25], v[68:69], v[20:21]
	v_pk_mul_f32 v[26:27], v[70:71], v[22:23]
	global_store_dwordx4 v[14:15], v[24:27], off offset:-2048
	v_lshlrev_b32_e32 v28, 16, v46
	v_and_b32_e32 v29, 0xffff0000, v46
	v_lshlrev_b32_e32 v30, 16, v47
	v_and_b32_e32 v31, 0xffff0000, v47
	v_pk_mul_f32 v[28:29], v[0:1], v[28:29] op_sel_hi:[0,1]
	v_pk_mul_f32 v[30:31], v[0:1], v[30:31] op_sel_hi:[0,1]
	v_pk_mul_f32 v[32:33], v[72:73], v[28:29]
	v_pk_mul_f32 v[34:35], v[74:75], v[30:31]
	global_store_dwordx4 v[14:15], v[32:35], off offset:-2032
	v_lshlrev_b32_e32 v20, 16, v48
	v_and_b32_e32 v21, 0xffff0000, v48
	v_lshlrev_b32_e32 v22, 16, v49
	v_and_b32_e32 v23, 0xffff0000, v49
	v_pk_mul_f32 v[20:21], v[0:1], v[20:21] op_sel_hi:[0,1]
	v_pk_mul_f32 v[22:23], v[0:1], v[22:23] op_sel_hi:[0,1]
	v_pk_mul_f32 v[24:25], v[76:77], v[20:21]
	v_pk_mul_f32 v[26:27], v[78:79], v[22:23]
	global_store_dwordx4 v[14:15], v[24:27], off
	v_lshlrev_b32_e32 v28, 16, v50
	v_and_b32_e32 v29, 0xffff0000, v50
	v_lshlrev_b32_e32 v30, 16, v51
	v_and_b32_e32 v31, 0xffff0000, v51
	v_pk_mul_f32 v[28:29], v[0:1], v[28:29] op_sel_hi:[0,1]
	v_pk_mul_f32 v[30:31], v[0:1], v[30:31] op_sel_hi:[0,1]
	v_pk_mul_f32 v[32:33], v[80:81], v[28:29]
	v_pk_mul_f32 v[34:35], v[82:83], v[30:31]
	global_store_dwordx4 v[14:15], v[32:35], off offset:16
	v_lshlrev_b32_e32 v20, 16, v52
	v_and_b32_e32 v21, 0xffff0000, v52
	v_lshlrev_b32_e32 v22, 16, v53
	v_and_b32_e32 v23, 0xffff0000, v53
	v_pk_mul_f32 v[20:21], v[0:1], v[20:21] op_sel_hi:[0,1]
	v_pk_mul_f32 v[22:23], v[0:1], v[22:23] op_sel_hi:[0,1]
	v_pk_mul_f32 v[24:25], v[84:85], v[20:21]
	v_pk_mul_f32 v[26:27], v[86:87], v[22:23]
	global_store_dwordx4 v[14:15], v[24:27], off offset:2048
	v_lshlrev_b32_e32 v28, 16, v54
	v_and_b32_e32 v29, 0xffff0000, v54
	v_lshlrev_b32_e32 v30, 16, v55
	v_and_b32_e32 v31, 0xffff0000, v55
	v_pk_mul_f32 v[28:29], v[0:1], v[28:29] op_sel_hi:[0,1]
	v_pk_mul_f32 v[30:31], v[0:1], v[30:31] op_sel_hi:[0,1]
	v_pk_mul_f32 v[32:33], v[88:89], v[28:29]
	v_pk_mul_f32 v[34:35], v[90:91], v[30:31]
	global_store_dwordx4 v[14:15], v[32:35], off offset:2064
	v_lshl_add_u64 v[14:15], v[14:15], 0, s[2:3]
	s_andn2_b64 exec, exec, s[6:7]
	s_cbranch_execnz .LBB0_719
